# X4 MLA queues: after the first empty fetch thread 0 peeks all 8 queue counters once and skips the atomic on queues already known empty (on v64)
# baseline (speedup 1.0000x reference)
; __global__ void __launch_bounds__(256, 2) mega(Params pk) {
;     ...
;       {
;         PP_
;         int* cb = (int*)(p.ws + OFF_CNT) + 64 + (layer * 2 + grp) * 32 + 16;
;         const int lgq = grp ? 4 : 7;
;         for (int xo = 0; xo < 8; ++xo) {
;           const int xq = (blockIdx.x + xo) & 7;
.LBB0_833:
	s_or_b64 exec, exec, s[6:7]
	s_mov_b64 s[6:7], s[94:95]
	s_waitcnt lgkmcnt(0)
	s_barrier
	s_load_dwordx2 s[6:7], s[6:7], 0x100
	s_add_i32 s40, s88, -2
	s_mov_b32 s49, 0
	s_mov_b32 s100, 0
	s_mov_b32 s101, 0
	s_waitcnt lgkmcnt(0)
	s_add_u32 s0, s6, s0
	s_addc_u32 s1, s7, s1
	s_add_u32 s41, s0, 0x3f00140
	s_addc_u32 s44, s1, 0
	s_add_u32 s0, s6, 0x1a000000
	s_addc_u32 s1, s7, 0
	s_add_u32 s45, s6, 0x1b800000
	s_addc_u32 s46, s7, 0
	s_add_u32 s47, s6, 0x1d000000
	s_addc_u32 s48, s7, 0
	s_add_u32 s24, s6, 0x4000000
	s_addc_u32 s25, s7, 0
	s_branch .LBB0_835

; __global__ void __launch_bounds__(256, 2) mega(Params pk) {
;     ...
;           for (;;) {
;             __syncthreads();
;             if (threadIdx.x == 0) s_item = atomicAdd(cb + xq, 1);
;             __syncthreads();
;             const int j = __builtin_amdgcn_readfirstlane(s_item);
;             if (j >= 128) break;
.LBB0_838:
	s_barrier
	s_and_saveexec_b64 s[6:7], s[4:5]
	s_cbranch_execz .LBB0_842
	s_mov_b64 s[38:39], exec
	v_mbcnt_lo_u32_b32 v0, s38, 0
	v_mbcnt_hi_u32_b32 v0, s39, v0
	v_cmp_eq_u32_e32 vcc, 0, v0
	s_and_saveexec_b64 s[8:9], vcc
	s_cbranch_execz .LBB0_841
	s_bcnt1_i32_b64 s28, s[38:39]
	v_mov_b32_e32 v2, s28
	s_bitcmp1_b32 s100, s50
	s_cbranch_scc1 .Lmq_skip
	global_atomic_add v2, v1, v2, s[34:35] sc0
	s_waitcnt vmcnt(0)
	v_readfirstlane_b32 s28, v2
	s_cmpk_lt_i32 s28, 0x80
	s_cbranch_scc1 .LBB0_841
	s_cmp_lg_u32 s101, 0
	s_cbranch_scc1 .LBB0_841
	s_mov_b32 s101, 1
	v_mov_b32_e32 v250, s41
	v_mov_b32_e32 v251, s44
	global_load_dwordx4 v[4:7], v[250:251], off sc1
	global_load_dwordx4 v[8:11], v[250:251], off offset:16 sc1
	s_waitcnt vmcnt(0)
	v_cmp_lt_u32_e32 vcc, 0x7f, v4
	s_and_b32 s28, vcc_lo, 1
	s_lshl_b32 s28, s28, 0
	s_or_b32 s100, s100, s28
	v_cmp_lt_u32_e32 vcc, 0x7f, v5
	s_and_b32 s28, vcc_lo, 1
	s_lshl_b32 s28, s28, 1
	s_or_b32 s100, s100, s28
	v_cmp_lt_u32_e32 vcc, 0x7f, v6
	s_and_b32 s28, vcc_lo, 1
	s_lshl_b32 s28, s28, 2
	s_or_b32 s100, s100, s28
	v_cmp_lt_u32_e32 vcc, 0x7f, v7
	s_and_b32 s28, vcc_lo, 1
	s_lshl_b32 s28, s28, 3
	s_or_b32 s100, s100, s28
	v_cmp_lt_u32_e32 vcc, 0x7f, v8
	s_and_b32 s28, vcc_lo, 1
	s_lshl_b32 s28, s28, 4
	s_or_b32 s100, s100, s28
	v_cmp_lt_u32_e32 vcc, 0x7f, v9
	s_and_b32 s28, vcc_lo, 1
	s_lshl_b32 s28, s28, 5
	s_or_b32 s100, s100, s28
	v_cmp_lt_u32_e32 vcc, 0x7f, v10
	s_and_b32 s28, vcc_lo, 1
	s_lshl_b32 s28, s28, 6
	s_or_b32 s100, s100, s28
	v_cmp_lt_u32_e32 vcc, 0x7f, v11
	s_and_b32 s28, vcc_lo, 1
	s_lshl_b32 s28, s28, 7
	s_or_b32 s100, s100, s28
	s_branch .LBB0_841
.Lmq_skip:
	v_mov_b32_e32 v2, 0x80
